# SSM chunk scan rewritten: S rows staged to LDS by all 8 waves via LDS-DMA, serial scan reads LDS
# speedup vs baseline: 1.0088x; 1.0051x over previous
; __device__ __forceinline__ void scan_phase(const Ctx& X, const float* S, const float* AT, bf16_t* A2) {
;     if (X.tid >= 128) return;
;     const int id = X.bx * 128 + X.tid; if (id >= 8 * 32 * 128) return;
;     const int p = id & 63, dir = (id >> 6) & 1, g = (id >> 7) & 31, b = id >> 12;
;     const float ar = AT[((g * 2 + dir) * 64 + p) * 2], ai = AT[((g * 2 + dir) * 64 + p) * 2 + 1];
;     const float* Sg = S + (size_t)g * A2ROWS * 256 + dir * 128 + p; bf16_t* Hg = A2 + (size_t)g * A2ROWS * A2K + 512 + dir * 128 + p;
;     float hr = 0.f, hi = 0.f;
;     { float sr[8], si[8];
; #pragma unroll
;         for (int c = 0; c < 8; ++c) { const int cc = dir == 0 ? c : 7 - c; const size_t n = 1024 + 8 * b + cc; sr[c] = Sg[n * 256]; si[c] = Sg[n * 256 + 64]; }
; #pragma unroll
;         for (int c = 0; c < 8; ++c) { const float t = ar * hr - ai * hi + sr[c]; hi = ar * hi + ai * hr + si[c]; hr = t; } }
.LBB0_692:
	s_or_b64 exec, exec, s[4:5]
	s_waitcnt lgkmcnt(0)
	v_mov_b32_e32 v0, v206
	s_movk_i32 s4, 0x80
	s_barrier
	v_readfirstlane_b32 s12, v206
	s_lshr_b32 s12, s12, 6
	v_and_b32_e32 v1, 63, v206
	s_and_b32 s0, s2, 31
	s_lshr_b32 s1, s2, 5
	s_mul_i32 s4, s0, 0x140000
	s_add_u32 s36, s88, s4
	s_addc_u32 s37, s89, 0
	s_add_u32 s36, s36, 0xe500000
	s_addc_u32 s37, s37, 0
	v_and_b32_e32 v2, 31, v1
	v_lshlrev_b32_e32 v2, 4, v2
	v_lshrrev_b32_e32 v3, 5, v1
	v_lshlrev_b32_e32 v3, 10, v3
	v_add_u32_e32 v4, v2, v3
	v_sub_u32_e32 v5, 0x400, v3
	v_add_u32_e32 v5, v2, v5
	s_mov_b32 s33, s12
.Lat_sdma:
	s_cmp_ge_u32 s33, 0x44
	s_cselect_b32 s4, 1, 0
	s_mul_i32 s5, s4, 0x44
	s_sub_u32 s5, s33, s5
	s_lshl_b32 s6, s5, 1
	s_cmp_lt_u32 s6, 8
	s_cbranch_scc0 .Lat_sdma_lat
	s_sub_u32 s7, 7, s6
	s_cmp_eq_u32 s4, 0
	s_cselect_b32 s7, s6, s7
	s_lshl_b32 s8, s1, 3
	s_add_u32 s7, s7, s8
	s_add_u32 s7, s7, 0x400
	s_branch .Lat_sdma_n
.Lat_sdma_lat:
	s_sub_u32 s7, s6, 8
	s_sub_u32 s8, 0x7f, s7
	s_cmp_eq_u32 s4, 0
	s_cselect_b32 s7, s7, s8
	s_lshl_b32 s8, s1, 7
	s_add_u32 s7, s7, s8
.Lat_sdma_n:
	s_sub_u32 s7, s7, s4
	s_lshl_b32 s7, s7, 10
	s_lshl_b32 s8, s4, 9
	s_add_u32 s7, s7, s8
	s_add_u32 s40, s36, s7
	s_addc_u32 s41, s37, 0
	s_mul_i32 s8, s4, 0x11000
	s_lshl_b32 s9, s5, 10
	s_add_u32 s8, s8, s9
	s_mov_b32 m0, s8
	s_cmp_eq_u32 s4, 0
	s_cbranch_scc0 .Lat_sdma_t1
	global_load_lds_dwordx4 v4, s[40:41]
	s_branch .Lat_sdma_nx
.Lat_sdma_t1:
	s_nop 0
	global_load_lds_dwordx4 v5, s[40:41]
.Lat_sdma_nx:
	s_add_u32 s33, s33, 8
	s_cmp_lt_u32 s33, 0x88
	s_cbranch_scc1 .Lat_sdma
	v_readlane_b32 s46, v254, 4
	v_readlane_b32 s47, v254, 5
	s_and_b32 s44, s2, 31
	s_lshl_b32 s44, s44, 1
	s_and_b32 s7, s12, 1
	s_add_u32 s44, s44, s7
	s_lshl_b32 s44, s44, 9
	s_add_u32 s46, s46, s44
	s_addc_u32 s47, s47, 0
	v_lshlrev_b32_e32 v84, 3, v1
	global_load_dwordx2 v[92:93], v84, s[46:47]
	s_waitcnt vmcnt(0) lgkmcnt(0)
	s_barrier
	s_cmp_lt_u32 s12, 2
	s_cbranch_scc0 .Lat_scan_done
	s_and_b32 s0, s2, 31
	s_lshr_b32 s1, s2, 5
	s_mul_i32 s4, s0, 0x1e0000
	s_add_u32 s40, s88, s4
	s_addc_u32 s41, s89, 0
	s_lshl_b32 s4, s1, 7
	s_mul_i32 s5, s12, 0x7f
	s_add_u32 s4, s4, s5
	s_mul_i32 s4, s4, 0x600
	s_lshl_b32 s5, s12, 8
	s_add_u32 s4, s4, s5
	s_add_u32 s4, s4, 0xa900400
	s_add_u32 s40, s40, s4
	s_addc_u32 s41, s41, 0
	s_mov_b32 s42, 0x600
	s_mov_b32 s43, 0
	s_cmp_eq_u32 s12, 0
	s_cbranch_scc1 .Lat_scan_fwd
	s_mov_b32 s42, 0xfffffa00
	s_mov_b32 s43, -1
.Lat_scan_fwd:
	s_mul_i32 s4, s12, 0x11000
	v_lshl_add_u32 v94, v1, 2, s4
	v_add_u32_e32 v95, 0x10000, v94
	v_lshlrev_b32_e32 v96, 1, v1
	v_mov_b32_e32 v98, 0
	v_mov_b32_e32 v99, 0
	ds_read2st64_b32 v[104:105], v94 offset0:0 offset1:1
	ds_read2st64_b32 v[106:107], v94 offset0:2 offset1:3
	ds_read2st64_b32 v[108:109], v94 offset0:4 offset1:5
	ds_read2st64_b32 v[110:111], v94 offset0:6 offset1:7
	ds_read2st64_b32 v[112:113], v94 offset0:8 offset1:9
	ds_read2st64_b32 v[114:115], v94 offset0:10 offset1:11
	ds_read2st64_b32 v[116:117], v94 offset0:12 offset1:13
	s_waitcnt lgkmcnt(6)
	v_fma_f32 v120, v92, v98, v104
	v_fma_f32 v121, v92, v99, v105
	v_fma_f32 v100, -v93, v99, v120
	v_fma_f32 v101, v93, v98, v121
	ds_read2st64_b32 v[118:119], v94 offset0:14 offset1:15
	s_waitcnt lgkmcnt(6)
	v_fma_f32 v120, v92, v100, v106
	v_fma_f32 v121, v92, v101, v107
	v_fma_f32 v98, -v93, v101, v120
	v_fma_f32 v99, v93, v100, v121
	ds_read2st64_b32 v[104:105], v94 offset0:16 offset1:17
	s_waitcnt lgkmcnt(6)
	v_fma_f32 v120, v92, v98, v108
	v_fma_f32 v121, v92, v99, v109
	v_fma_f32 v100, -v93, v99, v120
	v_fma_f32 v101, v93, v98, v121
	ds_read2st64_b32 v[106:107], v94 offset0:18 offset1:19
	s_waitcnt lgkmcnt(6)
	v_fma_f32 v120, v92, v100, v110
	v_fma_f32 v121, v92, v101, v111
	v_fma_f32 v98, -v93, v101, v120
	v_fma_f32 v99, v93, v100, v121
	ds_read2st64_b32 v[108:109], v94 offset0:20 offset1:21
	s_waitcnt lgkmcnt(6)
	v_fma_f32 v120, v92, v98, v112
	v_fma_f32 v121, v92, v99, v113
	v_fma_f32 v100, -v93, v99, v120
	v_fma_f32 v101, v93, v98, v121
	ds_read2st64_b32 v[110:111], v94 offset0:22 offset1:23
	s_waitcnt lgkmcnt(6)
	v_fma_f32 v120, v92, v100, v114
	v_fma_f32 v121, v92, v101, v115
	v_fma_f32 v98, -v93, v101, v120
	v_fma_f32 v99, v93, v100, v121
	ds_read2st64_b32 v[112:113], v94 offset0:24 offset1:25
	s_waitcnt lgkmcnt(6)
	v_fma_f32 v120, v92, v98, v116
	v_fma_f32 v121, v92, v99, v117
	v_fma_f32 v100, -v93, v99, v120
	v_fma_f32 v101, v93, v98, v121
	ds_read2st64_b32 v[114:115], v94 offset0:26 offset1:27
	s_waitcnt lgkmcnt(6)
	v_fma_f32 v120, v92, v100, v118
	v_fma_f32 v121, v92, v101, v119
	v_fma_f32 v98, -v93, v101, v120
	v_fma_f32 v99, v93, v100, v121
	ds_read2st64_b32 v[116:117], v94 offset0:28 offset1:29
	s_waitcnt lgkmcnt(6)
	v_cvt_pk_bf16_f32 v97, v98, v99
	s_nop 0
	global_store_short v96, v97, s[40:41]
	global_store_short_d16_hi v96, v97, s[40:41] offset:128
	s_add_u32 s40, s40, s42
	s_addc_u32 s41, s41, s43
	v_fma_f32 v120, v92, v98, v104
	v_fma_f32 v121, v92, v99, v105
	v_fma_f32 v100, -v93, v99, v120
	v_fma_f32 v101, v93, v98, v121
	ds_read2st64_b32 v[118:119], v94 offset0:30 offset1:31
	s_waitcnt lgkmcnt(6)
	v_cvt_pk_bf16_f32 v97, v100, v101
	s_nop 0
	global_store_short v96, v97, s[40:41]
	global_store_short_d16_hi v96, v97, s[40:41] offset:128
	s_add_u32 s40, s40, s42
	s_addc_u32 s41, s41, s43
	v_fma_f32 v120, v92, v100, v106
	v_fma_f32 v121, v92, v101, v107
	v_fma_f32 v98, -v93, v101, v120
	v_fma_f32 v99, v93, v100, v121
	ds_read2st64_b32 v[104:105], v94 offset0:32 offset1:33
	s_waitcnt lgkmcnt(6)
; __device__ __forceinline__ bf16_t f2bf(float f) { return (bf16_t)(cvt_pk_bf16(f, 0.f) & 0xffffu); }
; __device__ __forceinline__ void scan_phase(const Ctx& X, const float* S, const float* AT, bf16_t* A2) {
;     ...
;     for (int c0 = 0; c0 < 128; c0 += 16) { float sr[16], si[16];
; #pragma unroll
;         for (int c = 0; c < 16; ++c) { const int cc = dir == 0 ? c0 + c : 127 - c0 - c; const size_t n = 128 * b + cc; sr[c] = Sg[n * 256]; si[c] = Sg[n * 256 + 64]; }
; #pragma unroll
;         for (int c = 0; c < 16; ++c) { const int cc = dir == 0 ? c0 + c : 127 - c0 - c; const size_t n = 128 * b + cc;
;             Hg[n * A2K] = f2bf(hr); Hg[n * A2K + 64] = f2bf(hi);
;             const float t = ar * hr - ai * hi + sr[c]; hi = ar * hi + ai * hr + si[c]; hr = t; } }
	v_cvt_pk_bf16_f32 v97, v98, v99
	s_nop 0
	global_store_short v96, v97, s[40:41]
	global_store_short_d16_hi v96, v97, s[40:41] offset:128
	s_add_u32 s40, s40, s42
	s_addc_u32 s41, s41, s43
	v_fma_f32 v120, v92, v98, v108
	v_fma_f32 v121, v92, v99, v109
	v_fma_f32 v100, -v93, v99, v120
	v_fma_f32 v101, v93, v98, v121
	ds_read2st64_b32 v[106:107], v94 offset0:34 offset1:35
	s_waitcnt lgkmcnt(6)
	v_cvt_pk_bf16_f32 v97, v100, v101
	s_nop 0
	global_store_short v96, v97, s[40:41]
	global_store_short_d16_hi v96, v97, s[40:41] offset:128
	s_add_u32 s40, s40, s42
	s_addc_u32 s41, s41, s43
	v_fma_f32 v120, v92, v100, v110
	v_fma_f32 v121, v92, v101, v111
	v_fma_f32 v98, -v93, v101, v120
	v_fma_f32 v99, v93, v100, v121
	ds_read2st64_b32 v[108:109], v94 offset0:36 offset1:37
	s_waitcnt lgkmcnt(6)
	v_cvt_pk_bf16_f32 v97, v98, v99
	s_nop 0
	global_store_short v96, v97, s[40:41]
	global_store_short_d16_hi v96, v97, s[40:41] offset:128
	s_add_u32 s40, s40, s42
	s_addc_u32 s41, s41, s43
	v_fma_f32 v120, v92, v98, v112
	v_fma_f32 v121, v92, v99, v113
	v_fma_f32 v100, -v93, v99, v120
	v_fma_f32 v101, v93, v98, v121
	ds_read2st64_b32 v[110:111], v94 offset0:38 offset1:39
	s_waitcnt lgkmcnt(6)
	v_cvt_pk_bf16_f32 v97, v100, v101
	s_nop 0
	global_store_short v96, v97, s[40:41]
	global_store_short_d16_hi v96, v97, s[40:41] offset:128
	s_add_u32 s40, s40, s42
	s_addc_u32 s41, s41, s43
	v_fma_f32 v120, v92, v100, v114
	v_fma_f32 v121, v92, v101, v115
	v_fma_f32 v98, -v93, v101, v120
	v_fma_f32 v99, v93, v100, v121
	ds_read2st64_b32 v[112:113], v94 offset0:40 offset1:41
	s_waitcnt lgkmcnt(6)
	v_cvt_pk_bf16_f32 v97, v98, v99
	s_nop 0
	global_store_short v96, v97, s[40:41]
	global_store_short_d16_hi v96, v97, s[40:41] offset:128
	s_add_u32 s40, s40, s42
	s_addc_u32 s41, s41, s43
	v_fma_f32 v120, v92, v98, v116
	v_fma_f32 v121, v92, v99, v117
	v_fma_f32 v100, -v93, v99, v120
	v_fma_f32 v101, v93, v98, v121
	ds_read2st64_b32 v[114:115], v94 offset0:42 offset1:43
	s_waitcnt lgkmcnt(6)
	v_cvt_pk_bf16_f32 v97, v100, v101
	s_nop 0
	global_store_short v96, v97, s[40:41]
	global_store_short_d16_hi v96, v97, s[40:41] offset:128
	s_add_u32 s40, s40, s42
	s_addc_u32 s41, s41, s43
	v_fma_f32 v120, v92, v100, v118
	v_fma_f32 v121, v92, v101, v119
	v_fma_f32 v98, -v93, v101, v120
	v_fma_f32 v99, v93, v100, v121
	ds_read2st64_b32 v[116:117], v94 offset0:44 offset1:45
	s_waitcnt lgkmcnt(6)
	v_cvt_pk_bf16_f32 v97, v98, v99
	s_nop 0
	global_store_short v96, v97, s[40:41]
	global_store_short_d16_hi v96, v97, s[40:41] offset:128
	s_add_u32 s40, s40, s42
	s_addc_u32 s41, s41, s43
	v_fma_f32 v120, v92, v98, v104
	v_fma_f32 v121, v92, v99, v105
	v_fma_f32 v100, -v93, v99, v120
	v_fma_f32 v101, v93, v98, v121
	ds_read2st64_b32 v[118:119], v94 offset0:46 offset1:47
	s_waitcnt lgkmcnt(6)
	v_cvt_pk_bf16_f32 v97, v100, v101
	s_nop 0
	global_store_short v96, v97, s[40:41]
	global_store_short_d16_hi v96, v97, s[40:41] offset:128
	s_add_u32 s40, s40, s42
	s_addc_u32 s41, s41, s43
	v_fma_f32 v120, v92, v100, v106
	v_fma_f32 v121, v92, v101, v107
	v_fma_f32 v98, -v93, v101, v120
	v_fma_f32 v99, v93, v100, v121
	ds_read2st64_b32 v[104:105], v94 offset0:48 offset1:49
	s_waitcnt lgkmcnt(6)
	v_cvt_pk_bf16_f32 v97, v98, v99
	s_nop 0
	global_store_short v96, v97, s[40:41]
	global_store_short_d16_hi v96, v97, s[40:41] offset:128
	s_add_u32 s40, s40, s42
	s_addc_u32 s41, s41, s43
	v_fma_f32 v120, v92, v98, v108
	v_fma_f32 v121, v92, v99, v109
	v_fma_f32 v100, -v93, v99, v120
	v_fma_f32 v101, v93, v98, v121
	ds_read2st64_b32 v[106:107], v94 offset0:50 offset1:51
	s_waitcnt lgkmcnt(6)
	v_cvt_pk_bf16_f32 v97, v100, v101
	s_nop 0
	global_store_short v96, v97, s[40:41]
	global_store_short_d16_hi v96, v97, s[40:41] offset:128
	s_add_u32 s40, s40, s42
	s_addc_u32 s41, s41, s43
	v_fma_f32 v120, v92, v100, v110
	v_fma_f32 v121, v92, v101, v111
	v_fma_f32 v98, -v93, v101, v120
	v_fma_f32 v99, v93, v100, v121
	ds_read2st64_b32 v[108:109], v94 offset0:52 offset1:53
	s_waitcnt lgkmcnt(6)
	v_cvt_pk_bf16_f32 v97, v98, v99
	s_nop 0
	global_store_short v96, v97, s[40:41]
	global_store_short_d16_hi v96, v97, s[40:41] offset:128
	s_add_u32 s40, s40, s42
	s_addc_u32 s41, s41, s43
	v_fma_f32 v120, v92, v98, v112
	v_fma_f32 v121, v92, v99, v113
	v_fma_f32 v100, -v93, v99, v120
	v_fma_f32 v101, v93, v98, v121
	ds_read2st64_b32 v[110:111], v94 offset0:54 offset1:55
	s_waitcnt lgkmcnt(6)
	v_cvt_pk_bf16_f32 v97, v100, v101
	s_nop 0
	global_store_short v96, v97, s[40:41]
	global_store_short_d16_hi v96, v97, s[40:41] offset:128
	s_add_u32 s40, s40, s42
	s_addc_u32 s41, s41, s43
	v_fma_f32 v120, v92, v100, v114
	v_fma_f32 v121, v92, v101, v115
	v_fma_f32 v98, -v93, v101, v120
	v_fma_f32 v99, v93, v100, v121
	ds_read2st64_b32 v[112:113], v94 offset0:56 offset1:57
	s_waitcnt lgkmcnt(6)
	v_cvt_pk_bf16_f32 v97, v98, v99
	s_nop 0
	global_store_short v96, v97, s[40:41]
	global_store_short_d16_hi v96, v97, s[40:41] offset:128
	s_add_u32 s40, s40, s42
	s_addc_u32 s41, s41, s43
	v_fma_f32 v120, v92, v98, v116
	v_fma_f32 v121, v92, v99, v117
	v_fma_f32 v100, -v93, v99, v120
	v_fma_f32 v101, v93, v98, v121
	ds_read2st64_b32 v[114:115], v94 offset0:58 offset1:59
	s_waitcnt lgkmcnt(6)
	v_cvt_pk_bf16_f32 v97, v100, v101
	s_nop 0
	global_store_short v96, v97, s[40:41]
	global_store_short_d16_hi v96, v97, s[40:41] offset:128
	s_add_u32 s40, s40, s42
	s_addc_u32 s41, s41, s43
	v_fma_f32 v120, v92, v100, v118
	v_fma_f32 v121, v92, v101, v119
	v_fma_f32 v98, -v93, v101, v120
	v_fma_f32 v99, v93, v100, v121
	ds_read2st64_b32 v[116:117], v94 offset0:60 offset1:61
	s_waitcnt lgkmcnt(6)
; __device__ __forceinline__ bf16_t f2bf(float f) { return (bf16_t)(cvt_pk_bf16(f, 0.f) & 0xffffu); }
; __device__ __forceinline__ void scan_phase(const Ctx& X, const float* S, const float* AT, bf16_t* A2) {
;     ...
;     for (int c0 = 0; c0 < 128; c0 += 16) { float sr[16], si[16];
; #pragma unroll
;         for (int c = 0; c < 16; ++c) { const int cc = dir == 0 ? c0 + c : 127 - c0 - c; const size_t n = 128 * b + cc; sr[c] = Sg[n * 256]; si[c] = Sg[n * 256 + 64]; }
; #pragma unroll
;         for (int c = 0; c < 16; ++c) { const int cc = dir == 0 ? c0 + c : 127 - c0 - c; const size_t n = 128 * b + cc;
;             Hg[n * A2K] = f2bf(hr); Hg[n * A2K + 64] = f2bf(hi);
;             const float t = ar * hr - ai * hi + sr[c]; hi = ar * hi + ai * hr + si[c]; hr = t; } }
	v_cvt_pk_bf16_f32 v97, v98, v99
	s_nop 0
	global_store_short v96, v97, s[40:41]
	global_store_short_d16_hi v96, v97, s[40:41] offset:128
	s_add_u32 s40, s40, s42
	s_addc_u32 s41, s41, s43
	v_fma_f32 v120, v92, v98, v104
	v_fma_f32 v121, v92, v99, v105
	v_fma_f32 v100, -v93, v99, v120
	v_fma_f32 v101, v93, v98, v121
	ds_read2st64_b32 v[118:119], v94 offset0:62 offset1:63
	s_waitcnt lgkmcnt(6)
	v_cvt_pk_bf16_f32 v97, v100, v101
	s_nop 0
	global_store_short v96, v97, s[40:41]
	global_store_short_d16_hi v96, v97, s[40:41] offset:128
	s_add_u32 s40, s40, s42
	s_addc_u32 s41, s41, s43
	v_fma_f32 v120, v92, v100, v106
	v_fma_f32 v121, v92, v101, v107
	v_fma_f32 v98, -v93, v101, v120
	v_fma_f32 v99, v93, v100, v121
	ds_read2st64_b32 v[104:105], v94 offset0:64 offset1:65
	s_waitcnt lgkmcnt(6)
	v_cvt_pk_bf16_f32 v97, v98, v99
	s_nop 0
	global_store_short v96, v97, s[40:41]
	global_store_short_d16_hi v96, v97, s[40:41] offset:128
	s_add_u32 s40, s40, s42
	s_addc_u32 s41, s41, s43
	v_fma_f32 v120, v92, v98, v108
	v_fma_f32 v121, v92, v99, v109
	v_fma_f32 v100, -v93, v99, v120
	v_fma_f32 v101, v93, v98, v121
	ds_read2st64_b32 v[106:107], v94 offset0:66 offset1:67
	s_waitcnt lgkmcnt(6)
	v_cvt_pk_bf16_f32 v97, v100, v101
	s_nop 0
	global_store_short v96, v97, s[40:41]
	global_store_short_d16_hi v96, v97, s[40:41] offset:128
	s_add_u32 s40, s40, s42
	s_addc_u32 s41, s41, s43
	v_fma_f32 v120, v92, v100, v110
	v_fma_f32 v121, v92, v101, v111
	v_fma_f32 v98, -v93, v101, v120
	v_fma_f32 v99, v93, v100, v121
	ds_read2st64_b32 v[108:109], v94 offset0:68 offset1:69
	s_waitcnt lgkmcnt(6)
	v_cvt_pk_bf16_f32 v97, v98, v99
	s_nop 0
	global_store_short v96, v97, s[40:41]
	global_store_short_d16_hi v96, v97, s[40:41] offset:128
	s_add_u32 s40, s40, s42
	s_addc_u32 s41, s41, s43
	v_fma_f32 v120, v92, v98, v112
	v_fma_f32 v121, v92, v99, v113
	v_fma_f32 v100, -v93, v99, v120
	v_fma_f32 v101, v93, v98, v121
	ds_read2st64_b32 v[110:111], v94 offset0:70 offset1:71
	s_waitcnt lgkmcnt(6)
	v_cvt_pk_bf16_f32 v97, v100, v101
	s_nop 0
	global_store_short v96, v97, s[40:41]
	global_store_short_d16_hi v96, v97, s[40:41] offset:128
	s_add_u32 s40, s40, s42
	s_addc_u32 s41, s41, s43
	v_fma_f32 v120, v92, v100, v114
	v_fma_f32 v121, v92, v101, v115
	v_fma_f32 v98, -v93, v101, v120
	v_fma_f32 v99, v93, v100, v121
	ds_read2st64_b32 v[112:113], v94 offset0:72 offset1:73
	s_waitcnt lgkmcnt(6)
	v_cvt_pk_bf16_f32 v97, v98, v99
	s_nop 0
	global_store_short v96, v97, s[40:41]
	global_store_short_d16_hi v96, v97, s[40:41] offset:128
	s_add_u32 s40, s40, s42
	s_addc_u32 s41, s41, s43
	v_fma_f32 v120, v92, v98, v116
	v_fma_f32 v121, v92, v99, v117
	v_fma_f32 v100, -v93, v99, v120
	v_fma_f32 v101, v93, v98, v121
	ds_read2st64_b32 v[114:115], v94 offset0:74 offset1:75
	s_waitcnt lgkmcnt(6)
	v_cvt_pk_bf16_f32 v97, v100, v101
	s_nop 0
	global_store_short v96, v97, s[40:41]
	global_store_short_d16_hi v96, v97, s[40:41] offset:128
	s_add_u32 s40, s40, s42
	s_addc_u32 s41, s41, s43
	v_fma_f32 v120, v92, v100, v118
	v_fma_f32 v121, v92, v101, v119
	v_fma_f32 v98, -v93, v101, v120
	v_fma_f32 v99, v93, v100, v121
	ds_read2st64_b32 v[116:117], v94 offset0:76 offset1:77
	s_waitcnt lgkmcnt(6)
	v_cvt_pk_bf16_f32 v97, v98, v99
	s_nop 0
	global_store_short v96, v97, s[40:41]
	global_store_short_d16_hi v96, v97, s[40:41] offset:128
	s_add_u32 s40, s40, s42
	s_addc_u32 s41, s41, s43
	v_fma_f32 v120, v92, v98, v104
	v_fma_f32 v121, v92, v99, v105
	v_fma_f32 v100, -v93, v99, v120
	v_fma_f32 v101, v93, v98, v121
	ds_read2st64_b32 v[118:119], v94 offset0:78 offset1:79
	s_waitcnt lgkmcnt(6)
	v_cvt_pk_bf16_f32 v97, v100, v101
	s_nop 0
	global_store_short v96, v97, s[40:41]
	global_store_short_d16_hi v96, v97, s[40:41] offset:128
	s_add_u32 s40, s40, s42
	s_addc_u32 s41, s41, s43
	v_fma_f32 v120, v92, v100, v106
	v_fma_f32 v121, v92, v101, v107
	v_fma_f32 v98, -v93, v101, v120
	v_fma_f32 v99, v93, v100, v121
	ds_read2st64_b32 v[104:105], v94 offset0:80 offset1:81
	s_waitcnt lgkmcnt(6)
	v_cvt_pk_bf16_f32 v97, v98, v99
	s_nop 0
	global_store_short v96, v97, s[40:41]
	global_store_short_d16_hi v96, v97, s[40:41] offset:128
	s_add_u32 s40, s40, s42
	s_addc_u32 s41, s41, s43
	v_fma_f32 v120, v92, v98, v108
	v_fma_f32 v121, v92, v99, v109
	v_fma_f32 v100, -v93, v99, v120
	v_fma_f32 v101, v93, v98, v121
	ds_read2st64_b32 v[106:107], v94 offset0:82 offset1:83
	s_waitcnt lgkmcnt(6)
	v_cvt_pk_bf16_f32 v97, v100, v101
	s_nop 0
	global_store_short v96, v97, s[40:41]
	global_store_short_d16_hi v96, v97, s[40:41] offset:128
	s_add_u32 s40, s40, s42
	s_addc_u32 s41, s41, s43
	v_fma_f32 v120, v92, v100, v110
	v_fma_f32 v121, v92, v101, v111
	v_fma_f32 v98, -v93, v101, v120
	v_fma_f32 v99, v93, v100, v121
	ds_read2st64_b32 v[108:109], v94 offset0:84 offset1:85
	s_waitcnt lgkmcnt(6)
	v_cvt_pk_bf16_f32 v97, v98, v99
	s_nop 0
	global_store_short v96, v97, s[40:41]
	global_store_short_d16_hi v96, v97, s[40:41] offset:128
	s_add_u32 s40, s40, s42
	s_addc_u32 s41, s41, s43
	v_fma_f32 v120, v92, v98, v112
	v_fma_f32 v121, v92, v99, v113
	v_fma_f32 v100, -v93, v99, v120
	v_fma_f32 v101, v93, v98, v121
	ds_read2st64_b32 v[110:111], v94 offset0:86 offset1:87
	s_waitcnt lgkmcnt(6)
	v_cvt_pk_bf16_f32 v97, v100, v101
	s_nop 0
	global_store_short v96, v97, s[40:41]
	global_store_short_d16_hi v96, v97, s[40:41] offset:128
	s_add_u32 s40, s40, s42
	s_addc_u32 s41, s41, s43
	v_fma_f32 v120, v92, v100, v114
	v_fma_f32 v121, v92, v101, v115
	v_fma_f32 v98, -v93, v101, v120
	v_fma_f32 v99, v93, v100, v121
	ds_read2st64_b32 v[112:113], v94 offset0:88 offset1:89
	s_waitcnt lgkmcnt(6)
; __device__ __forceinline__ bf16_t f2bf(float f) { return (bf16_t)(cvt_pk_bf16(f, 0.f) & 0xffffu); }
; __device__ __forceinline__ void scan_phase(const Ctx& X, const float* S, const float* AT, bf16_t* A2) {
;     ...
;     for (int c0 = 0; c0 < 128; c0 += 16) { float sr[16], si[16];
; #pragma unroll
;         for (int c = 0; c < 16; ++c) { const int cc = dir == 0 ? c0 + c : 127 - c0 - c; const size_t n = 128 * b + cc; sr[c] = Sg[n * 256]; si[c] = Sg[n * 256 + 64]; }
; #pragma unroll
;         for (int c = 0; c < 16; ++c) { const int cc = dir == 0 ? c0 + c : 127 - c0 - c; const size_t n = 128 * b + cc;
;             Hg[n * A2K] = f2bf(hr); Hg[n * A2K + 64] = f2bf(hi);
;             const float t = ar * hr - ai * hi + sr[c]; hi = ar * hi + ai * hr + si[c]; hr = t; } }
	v_cvt_pk_bf16_f32 v97, v98, v99
	s_nop 0
	global_store_short v96, v97, s[40:41]
	global_store_short_d16_hi v96, v97, s[40:41] offset:128
	s_add_u32 s40, s40, s42
	s_addc_u32 s41, s41, s43
	v_fma_f32 v120, v92, v98, v116
	v_fma_f32 v121, v92, v99, v117
	v_fma_f32 v100, -v93, v99, v120
	v_fma_f32 v101, v93, v98, v121
	ds_read2st64_b32 v[114:115], v94 offset0:90 offset1:91
	s_waitcnt lgkmcnt(6)
	v_cvt_pk_bf16_f32 v97, v100, v101
	s_nop 0
	global_store_short v96, v97, s[40:41]
	global_store_short_d16_hi v96, v97, s[40:41] offset:128
	s_add_u32 s40, s40, s42
	s_addc_u32 s41, s41, s43
	v_fma_f32 v120, v92, v100, v118
	v_fma_f32 v121, v92, v101, v119
	v_fma_f32 v98, -v93, v101, v120
	v_fma_f32 v99, v93, v100, v121
	ds_read2st64_b32 v[116:117], v94 offset0:92 offset1:93
	s_waitcnt lgkmcnt(6)
	v_cvt_pk_bf16_f32 v97, v98, v99
	s_nop 0
	global_store_short v96, v97, s[40:41]
	global_store_short_d16_hi v96, v97, s[40:41] offset:128
	s_add_u32 s40, s40, s42
	s_addc_u32 s41, s41, s43
	v_fma_f32 v120, v92, v98, v104
	v_fma_f32 v121, v92, v99, v105
	v_fma_f32 v100, -v93, v99, v120
	v_fma_f32 v101, v93, v98, v121
	ds_read2st64_b32 v[118:119], v94 offset0:94 offset1:95
	s_waitcnt lgkmcnt(6)
	v_cvt_pk_bf16_f32 v97, v100, v101
	s_nop 0
	global_store_short v96, v97, s[40:41]
	global_store_short_d16_hi v96, v97, s[40:41] offset:128
	s_add_u32 s40, s40, s42
	s_addc_u32 s41, s41, s43
	v_fma_f32 v120, v92, v100, v106
	v_fma_f32 v121, v92, v101, v107
	v_fma_f32 v98, -v93, v101, v120
	v_fma_f32 v99, v93, v100, v121
	ds_read2st64_b32 v[104:105], v94 offset0:96 offset1:97
	s_waitcnt lgkmcnt(6)
	v_cvt_pk_bf16_f32 v97, v98, v99
	s_nop 0
	global_store_short v96, v97, s[40:41]
	global_store_short_d16_hi v96, v97, s[40:41] offset:128
	s_add_u32 s40, s40, s42
	s_addc_u32 s41, s41, s43
	v_fma_f32 v120, v92, v98, v108
	v_fma_f32 v121, v92, v99, v109
	v_fma_f32 v100, -v93, v99, v120
	v_fma_f32 v101, v93, v98, v121
	ds_read2st64_b32 v[106:107], v94 offset0:98 offset1:99
	s_waitcnt lgkmcnt(6)
	v_cvt_pk_bf16_f32 v97, v100, v101
	s_nop 0
	global_store_short v96, v97, s[40:41]
	global_store_short_d16_hi v96, v97, s[40:41] offset:128
	s_add_u32 s40, s40, s42
	s_addc_u32 s41, s41, s43
	v_fma_f32 v120, v92, v100, v110
	v_fma_f32 v121, v92, v101, v111
	v_fma_f32 v98, -v93, v101, v120
	v_fma_f32 v99, v93, v100, v121
	ds_read2st64_b32 v[108:109], v94 offset0:100 offset1:101
	s_waitcnt lgkmcnt(6)
	v_cvt_pk_bf16_f32 v97, v98, v99
	s_nop 0
	global_store_short v96, v97, s[40:41]
	global_store_short_d16_hi v96, v97, s[40:41] offset:128
	s_add_u32 s40, s40, s42
	s_addc_u32 s41, s41, s43
	v_fma_f32 v120, v92, v98, v112
	v_fma_f32 v121, v92, v99, v113
	v_fma_f32 v100, -v93, v99, v120
	v_fma_f32 v101, v93, v98, v121
	ds_read2st64_b32 v[110:111], v94 offset0:102 offset1:103
	s_waitcnt lgkmcnt(6)
	v_cvt_pk_bf16_f32 v97, v100, v101
	s_nop 0
	global_store_short v96, v97, s[40:41]
	global_store_short_d16_hi v96, v97, s[40:41] offset:128
	s_add_u32 s40, s40, s42
	s_addc_u32 s41, s41, s43
	v_fma_f32 v120, v92, v100, v114
	v_fma_f32 v121, v92, v101, v115
	v_fma_f32 v98, -v93, v101, v120
	v_fma_f32 v99, v93, v100, v121
	ds_read2st64_b32 v[112:113], v94 offset0:104 offset1:105
	s_waitcnt lgkmcnt(6)
	v_cvt_pk_bf16_f32 v97, v98, v99
	s_nop 0
	global_store_short v96, v97, s[40:41]
	global_store_short_d16_hi v96, v97, s[40:41] offset:128
	s_add_u32 s40, s40, s42
	s_addc_u32 s41, s41, s43
	v_fma_f32 v120, v92, v98, v116
	v_fma_f32 v121, v92, v99, v117
	v_fma_f32 v100, -v93, v99, v120
	v_fma_f32 v101, v93, v98, v121
	ds_read2st64_b32 v[114:115], v94 offset0:106 offset1:107
	s_waitcnt lgkmcnt(6)
	v_cvt_pk_bf16_f32 v97, v100, v101
	s_nop 0
	global_store_short v96, v97, s[40:41]
	global_store_short_d16_hi v96, v97, s[40:41] offset:128
	s_add_u32 s40, s40, s42
	s_addc_u32 s41, s41, s43
	v_fma_f32 v120, v92, v100, v118
	v_fma_f32 v121, v92, v101, v119
	v_fma_f32 v98, -v93, v101, v120
	v_fma_f32 v99, v93, v100, v121
	ds_read2st64_b32 v[116:117], v94 offset0:108 offset1:109
	s_waitcnt lgkmcnt(6)
	v_cvt_pk_bf16_f32 v97, v98, v99
	s_nop 0
	global_store_short v96, v97, s[40:41]
	global_store_short_d16_hi v96, v97, s[40:41] offset:128
	s_add_u32 s40, s40, s42
	s_addc_u32 s41, s41, s43
	v_fma_f32 v120, v92, v98, v104
	v_fma_f32 v121, v92, v99, v105
	v_fma_f32 v100, -v93, v99, v120
	v_fma_f32 v101, v93, v98, v121
	ds_read2st64_b32 v[118:119], v94 offset0:110 offset1:111
	s_waitcnt lgkmcnt(6)
	v_cvt_pk_bf16_f32 v97, v100, v101
	s_nop 0
	global_store_short v96, v97, s[40:41]
	global_store_short_d16_hi v96, v97, s[40:41] offset:128
	s_add_u32 s40, s40, s42
	s_addc_u32 s41, s41, s43
	v_fma_f32 v120, v92, v100, v106
	v_fma_f32 v121, v92, v101, v107
	v_fma_f32 v98, -v93, v101, v120
	v_fma_f32 v99, v93, v100, v121
	ds_read2st64_b32 v[104:105], v94 offset0:112 offset1:113
	s_waitcnt lgkmcnt(6)
	v_cvt_pk_bf16_f32 v97, v98, v99
	s_nop 0
	global_store_short v96, v97, s[40:41]
	global_store_short_d16_hi v96, v97, s[40:41] offset:128
	s_add_u32 s40, s40, s42
	s_addc_u32 s41, s41, s43
	v_fma_f32 v120, v92, v98, v108
	v_fma_f32 v121, v92, v99, v109
	v_fma_f32 v100, -v93, v99, v120
	v_fma_f32 v101, v93, v98, v121
	ds_read2st64_b32 v[106:107], v94 offset0:114 offset1:115
	s_waitcnt lgkmcnt(6)
	v_cvt_pk_bf16_f32 v97, v100, v101
	s_nop 0
	global_store_short v96, v97, s[40:41]
	global_store_short_d16_hi v96, v97, s[40:41] offset:128
	s_add_u32 s40, s40, s42
	s_addc_u32 s41, s41, s43
	v_fma_f32 v120, v92, v100, v110
	v_fma_f32 v121, v92, v101, v111
	v_fma_f32 v98, -v93, v101, v120
	v_fma_f32 v99, v93, v100, v121
	ds_read2st64_b32 v[108:109], v94 offset0:116 offset1:117
	s_waitcnt lgkmcnt(6)
; __device__ __forceinline__ bf16_t f2bf(float f) { return (bf16_t)(cvt_pk_bf16(f, 0.f) & 0xffffu); }
; __device__ __forceinline__ void scan_phase(const Ctx& X, const float* S, const float* AT, bf16_t* A2) {
;     ...
;     for (int c0 = 0; c0 < 128; c0 += 16) { float sr[16], si[16];
; #pragma unroll
;         for (int c = 0; c < 16; ++c) { const int cc = dir == 0 ? c0 + c : 127 - c0 - c; const size_t n = 128 * b + cc; sr[c] = Sg[n * 256]; si[c] = Sg[n * 256 + 64]; }
; #pragma unroll
;         for (int c = 0; c < 16; ++c) { const int cc = dir == 0 ? c0 + c : 127 - c0 - c; const size_t n = 128 * b + cc;
;             Hg[n * A2K] = f2bf(hr); Hg[n * A2K + 64] = f2bf(hi);
;             const float t = ar * hr - ai * hi + sr[c]; hi = ar * hi + ai * hr + si[c]; hr = t; } }
	v_cvt_pk_bf16_f32 v97, v98, v99
	s_nop 0
	global_store_short v96, v97, s[40:41]
	global_store_short_d16_hi v96, v97, s[40:41] offset:128
	s_add_u32 s40, s40, s42
	s_addc_u32 s41, s41, s43
	v_fma_f32 v120, v92, v98, v112
	v_fma_f32 v121, v92, v99, v113
	v_fma_f32 v100, -v93, v99, v120
	v_fma_f32 v101, v93, v98, v121
	ds_read2st64_b32 v[110:111], v94 offset0:118 offset1:119
	s_waitcnt lgkmcnt(6)
	v_cvt_pk_bf16_f32 v97, v100, v101
	s_nop 0
	global_store_short v96, v97, s[40:41]
	global_store_short_d16_hi v96, v97, s[40:41] offset:128
	s_add_u32 s40, s40, s42
	s_addc_u32 s41, s41, s43
	v_fma_f32 v120, v92, v100, v114
	v_fma_f32 v121, v92, v101, v115
	v_fma_f32 v98, -v93, v101, v120
	v_fma_f32 v99, v93, v100, v121
	ds_read2st64_b32 v[112:113], v94 offset0:120 offset1:121
	s_waitcnt lgkmcnt(6)
	v_cvt_pk_bf16_f32 v97, v98, v99
	s_nop 0
	global_store_short v96, v97, s[40:41]
	global_store_short_d16_hi v96, v97, s[40:41] offset:128
	s_add_u32 s40, s40, s42
	s_addc_u32 s41, s41, s43
	v_fma_f32 v120, v92, v98, v116
	v_fma_f32 v121, v92, v99, v117
	v_fma_f32 v100, -v93, v99, v120
	v_fma_f32 v101, v93, v98, v121
	ds_read2st64_b32 v[114:115], v94 offset0:122 offset1:123
	s_waitcnt lgkmcnt(6)
	v_cvt_pk_bf16_f32 v97, v100, v101
	s_nop 0
	global_store_short v96, v97, s[40:41]
	global_store_short_d16_hi v96, v97, s[40:41] offset:128
	s_add_u32 s40, s40, s42
	s_addc_u32 s41, s41, s43
	v_fma_f32 v120, v92, v100, v118
	v_fma_f32 v121, v92, v101, v119
	v_fma_f32 v98, -v93, v101, v120
	v_fma_f32 v99, v93, v100, v121
	ds_read2st64_b32 v[116:117], v94 offset0:124 offset1:125
	s_waitcnt lgkmcnt(6)
	v_cvt_pk_bf16_f32 v97, v98, v99
	s_nop 0
	global_store_short v96, v97, s[40:41]
	global_store_short_d16_hi v96, v97, s[40:41] offset:128
	s_add_u32 s40, s40, s42
	s_addc_u32 s41, s41, s43
	v_fma_f32 v120, v92, v98, v104
	v_fma_f32 v121, v92, v99, v105
	v_fma_f32 v100, -v93, v99, v120
	v_fma_f32 v101, v93, v98, v121
	ds_read2st64_b32 v[118:119], v94 offset0:126 offset1:127
	s_waitcnt lgkmcnt(6)
	v_cvt_pk_bf16_f32 v97, v100, v101
	s_nop 0
	global_store_short v96, v97, s[40:41]
	global_store_short_d16_hi v96, v97, s[40:41] offset:128
	s_add_u32 s40, s40, s42
	s_addc_u32 s41, s41, s43
	v_fma_f32 v120, v92, v100, v106
	v_fma_f32 v121, v92, v101, v107
	v_fma_f32 v98, -v93, v101, v120
	v_fma_f32 v99, v93, v100, v121
	ds_read2st64_b32 v[104:105], v94 offset0:128 offset1:129
	s_waitcnt lgkmcnt(6)
	v_cvt_pk_bf16_f32 v97, v98, v99
	s_nop 0
	global_store_short v96, v97, s[40:41]
	global_store_short_d16_hi v96, v97, s[40:41] offset:128
	s_add_u32 s40, s40, s42
	s_addc_u32 s41, s41, s43
	v_fma_f32 v120, v92, v98, v108
	v_fma_f32 v121, v92, v99, v109
	v_fma_f32 v100, -v93, v99, v120
	v_fma_f32 v101, v93, v98, v121
	ds_read2st64_b32 v[106:107], v94 offset0:130 offset1:131
	s_waitcnt lgkmcnt(6)
	v_cvt_pk_bf16_f32 v97, v100, v101
	s_nop 0
	global_store_short v96, v97, s[40:41]
	global_store_short_d16_hi v96, v97, s[40:41] offset:128
	s_add_u32 s40, s40, s42
	s_addc_u32 s41, s41, s43
	v_fma_f32 v120, v92, v100, v110
	v_fma_f32 v121, v92, v101, v111
	v_fma_f32 v98, -v93, v101, v120
	v_fma_f32 v99, v93, v100, v121
	ds_read2st64_b32 v[108:109], v94 offset0:132 offset1:133
	s_waitcnt lgkmcnt(6)
	v_cvt_pk_bf16_f32 v97, v98, v99
	s_nop 0
	global_store_short v96, v97, s[40:41]
	global_store_short_d16_hi v96, v97, s[40:41] offset:128
	s_add_u32 s40, s40, s42
	s_addc_u32 s41, s41, s43
	v_fma_f32 v120, v92, v98, v112
	v_fma_f32 v121, v92, v99, v113
	v_fma_f32 v100, -v93, v99, v120
	v_fma_f32 v101, v93, v98, v121
	ds_read2st64_b32 v[110:111], v94 offset0:134 offset1:135
	s_waitcnt lgkmcnt(6)
	v_cvt_pk_bf16_f32 v97, v100, v101
	s_nop 0
	global_store_short v96, v97, s[40:41]
	global_store_short_d16_hi v96, v97, s[40:41] offset:128
	s_add_u32 s40, s40, s42
	s_addc_u32 s41, s41, s43
	v_fma_f32 v120, v92, v100, v114
	v_fma_f32 v121, v92, v101, v115
	v_fma_f32 v98, -v93, v101, v120
	v_fma_f32 v99, v93, v100, v121
	ds_read2st64_b32 v[112:113], v94 offset0:136 offset1:137
	s_waitcnt lgkmcnt(6)
	v_cvt_pk_bf16_f32 v97, v98, v99
	s_nop 0
	global_store_short v96, v97, s[40:41]
	global_store_short_d16_hi v96, v97, s[40:41] offset:128
	s_add_u32 s40, s40, s42
	s_addc_u32 s41, s41, s43
	v_fma_f32 v120, v92, v98, v116
	v_fma_f32 v121, v92, v99, v117
	v_fma_f32 v100, -v93, v99, v120
	v_fma_f32 v101, v93, v98, v121
	ds_read2st64_b32 v[114:115], v94 offset0:138 offset1:139
	s_waitcnt lgkmcnt(6)
	v_cvt_pk_bf16_f32 v97, v100, v101
	s_nop 0
	global_store_short v96, v97, s[40:41]
	global_store_short_d16_hi v96, v97, s[40:41] offset:128
	s_add_u32 s40, s40, s42
	s_addc_u32 s41, s41, s43
	v_fma_f32 v120, v92, v100, v118
	v_fma_f32 v121, v92, v101, v119
	v_fma_f32 v98, -v93, v101, v120
	v_fma_f32 v99, v93, v100, v121
	ds_read2st64_b32 v[116:117], v94 offset0:140 offset1:141
	s_waitcnt lgkmcnt(6)
	v_cvt_pk_bf16_f32 v97, v98, v99
	s_nop 0
	global_store_short v96, v97, s[40:41]
	global_store_short_d16_hi v96, v97, s[40:41] offset:128
	s_add_u32 s40, s40, s42
	s_addc_u32 s41, s41, s43
	v_fma_f32 v120, v92, v98, v104
	v_fma_f32 v121, v92, v99, v105
	v_fma_f32 v100, -v93, v99, v120
	v_fma_f32 v101, v93, v98, v121
	ds_read2st64_b32 v[118:119], v94 offset0:142 offset1:143
	s_waitcnt lgkmcnt(6)
	v_cvt_pk_bf16_f32 v97, v100, v101
	s_nop 0
	global_store_short v96, v97, s[40:41]
	global_store_short_d16_hi v96, v97, s[40:41] offset:128
	s_add_u32 s40, s40, s42
	s_addc_u32 s41, s41, s43
	v_fma_f32 v120, v92, v100, v106
	v_fma_f32 v121, v92, v101, v107
	v_fma_f32 v98, -v93, v101, v120
	v_fma_f32 v99, v93, v100, v121
	ds_read2st64_b32 v[104:105], v94 offset0:144 offset1:145
	s_waitcnt lgkmcnt(6)
; __device__ __forceinline__ bf16_t f2bf(float f) { return (bf16_t)(cvt_pk_bf16(f, 0.f) & 0xffffu); }
; __device__ __forceinline__ void scan_phase(const Ctx& X, const float* S, const float* AT, bf16_t* A2) {
;     ...
;     for (int c0 = 0; c0 < 128; c0 += 16) { float sr[16], si[16];
; #pragma unroll
;         for (int c = 0; c < 16; ++c) { const int cc = dir == 0 ? c0 + c : 127 - c0 - c; const size_t n = 128 * b + cc; sr[c] = Sg[n * 256]; si[c] = Sg[n * 256 + 64]; }
; #pragma unroll
;         for (int c = 0; c < 16; ++c) { const int cc = dir == 0 ? c0 + c : 127 - c0 - c; const size_t n = 128 * b + cc;
;             Hg[n * A2K] = f2bf(hr); Hg[n * A2K + 64] = f2bf(hi);
;             const float t = ar * hr - ai * hi + sr[c]; hi = ar * hi + ai * hr + si[c]; hr = t; } }
	v_cvt_pk_bf16_f32 v97, v98, v99
	s_nop 0
	global_store_short v96, v97, s[40:41]
	global_store_short_d16_hi v96, v97, s[40:41] offset:128
	s_add_u32 s40, s40, s42
	s_addc_u32 s41, s41, s43
	v_fma_f32 v120, v92, v98, v108
	v_fma_f32 v121, v92, v99, v109
	v_fma_f32 v100, -v93, v99, v120
	v_fma_f32 v101, v93, v98, v121
	ds_read2st64_b32 v[106:107], v94 offset0:146 offset1:147
	s_waitcnt lgkmcnt(6)
	v_cvt_pk_bf16_f32 v97, v100, v101
	s_nop 0
	global_store_short v96, v97, s[40:41]
	global_store_short_d16_hi v96, v97, s[40:41] offset:128
	s_add_u32 s40, s40, s42
	s_addc_u32 s41, s41, s43
	v_fma_f32 v120, v92, v100, v110
	v_fma_f32 v121, v92, v101, v111
	v_fma_f32 v98, -v93, v101, v120
	v_fma_f32 v99, v93, v100, v121
	ds_read2st64_b32 v[108:109], v94 offset0:148 offset1:149
	s_waitcnt lgkmcnt(6)
	v_cvt_pk_bf16_f32 v97, v98, v99
	s_nop 0
	global_store_short v96, v97, s[40:41]
	global_store_short_d16_hi v96, v97, s[40:41] offset:128
	s_add_u32 s40, s40, s42
	s_addc_u32 s41, s41, s43
	v_fma_f32 v120, v92, v98, v112
	v_fma_f32 v121, v92, v99, v113
	v_fma_f32 v100, -v93, v99, v120
	v_fma_f32 v101, v93, v98, v121
	ds_read2st64_b32 v[110:111], v94 offset0:150 offset1:151
	s_waitcnt lgkmcnt(6)
	v_cvt_pk_bf16_f32 v97, v100, v101
	s_nop 0
	global_store_short v96, v97, s[40:41]
	global_store_short_d16_hi v96, v97, s[40:41] offset:128
	s_add_u32 s40, s40, s42
	s_addc_u32 s41, s41, s43
	v_fma_f32 v120, v92, v100, v114
	v_fma_f32 v121, v92, v101, v115
	v_fma_f32 v98, -v93, v101, v120
	v_fma_f32 v99, v93, v100, v121
	ds_read2st64_b32 v[112:113], v94 offset0:152 offset1:153
	s_waitcnt lgkmcnt(6)
	v_cvt_pk_bf16_f32 v97, v98, v99
	s_nop 0
	global_store_short v96, v97, s[40:41]
	global_store_short_d16_hi v96, v97, s[40:41] offset:128
	s_add_u32 s40, s40, s42
	s_addc_u32 s41, s41, s43
	v_fma_f32 v120, v92, v98, v116
	v_fma_f32 v121, v92, v99, v117
	v_fma_f32 v100, -v93, v99, v120
	v_fma_f32 v101, v93, v98, v121
	ds_read2st64_b32 v[114:115], v94 offset0:154 offset1:155
	s_waitcnt lgkmcnt(6)
	v_cvt_pk_bf16_f32 v97, v100, v101
	s_nop 0
	global_store_short v96, v97, s[40:41]
	global_store_short_d16_hi v96, v97, s[40:41] offset:128
	s_add_u32 s40, s40, s42
	s_addc_u32 s41, s41, s43
	v_fma_f32 v120, v92, v100, v118
	v_fma_f32 v121, v92, v101, v119
	v_fma_f32 v98, -v93, v101, v120
	v_fma_f32 v99, v93, v100, v121
	ds_read2st64_b32 v[116:117], v94 offset0:156 offset1:157
	s_waitcnt lgkmcnt(6)
	v_cvt_pk_bf16_f32 v97, v98, v99
	s_nop 0
	global_store_short v96, v97, s[40:41]
	global_store_short_d16_hi v96, v97, s[40:41] offset:128
	s_add_u32 s40, s40, s42
	s_addc_u32 s41, s41, s43
	v_fma_f32 v120, v92, v98, v104
	v_fma_f32 v121, v92, v99, v105
	v_fma_f32 v100, -v93, v99, v120
	v_fma_f32 v101, v93, v98, v121
	ds_read2st64_b32 v[118:119], v94 offset0:158 offset1:159
	s_waitcnt lgkmcnt(6)
	v_cvt_pk_bf16_f32 v97, v100, v101
	s_nop 0
	global_store_short v96, v97, s[40:41]
	global_store_short_d16_hi v96, v97, s[40:41] offset:128
	s_add_u32 s40, s40, s42
	s_addc_u32 s41, s41, s43
	v_fma_f32 v120, v92, v100, v106
	v_fma_f32 v121, v92, v101, v107
	v_fma_f32 v98, -v93, v101, v120
	v_fma_f32 v99, v93, v100, v121
	ds_read2st64_b32 v[104:105], v94 offset0:160 offset1:161
	s_waitcnt lgkmcnt(6)
	v_cvt_pk_bf16_f32 v97, v98, v99
	s_nop 0
	global_store_short v96, v97, s[40:41]
	global_store_short_d16_hi v96, v97, s[40:41] offset:128
	s_add_u32 s40, s40, s42
	s_addc_u32 s41, s41, s43
	v_fma_f32 v120, v92, v98, v108
	v_fma_f32 v121, v92, v99, v109
	v_fma_f32 v100, -v93, v99, v120
	v_fma_f32 v101, v93, v98, v121
	ds_read2st64_b32 v[106:107], v94 offset0:162 offset1:163
	s_waitcnt lgkmcnt(6)
	v_cvt_pk_bf16_f32 v97, v100, v101
	s_nop 0
	global_store_short v96, v97, s[40:41]
	global_store_short_d16_hi v96, v97, s[40:41] offset:128
	s_add_u32 s40, s40, s42
	s_addc_u32 s41, s41, s43
	v_fma_f32 v120, v92, v100, v110
	v_fma_f32 v121, v92, v101, v111
	v_fma_f32 v98, -v93, v101, v120
	v_fma_f32 v99, v93, v100, v121
	ds_read2st64_b32 v[108:109], v94 offset0:164 offset1:165
	s_waitcnt lgkmcnt(6)
	v_cvt_pk_bf16_f32 v97, v98, v99
	s_nop 0
	global_store_short v96, v97, s[40:41]
	global_store_short_d16_hi v96, v97, s[40:41] offset:128
	s_add_u32 s40, s40, s42
	s_addc_u32 s41, s41, s43
	v_fma_f32 v120, v92, v98, v112
	v_fma_f32 v121, v92, v99, v113
	v_fma_f32 v100, -v93, v99, v120
	v_fma_f32 v101, v93, v98, v121
	ds_read2st64_b32 v[110:111], v94 offset0:166 offset1:167
	s_waitcnt lgkmcnt(6)
	v_cvt_pk_bf16_f32 v97, v100, v101
	s_nop 0
	global_store_short v96, v97, s[40:41]
	global_store_short_d16_hi v96, v97, s[40:41] offset:128
	s_add_u32 s40, s40, s42
	s_addc_u32 s41, s41, s43
	v_fma_f32 v120, v92, v100, v114
	v_fma_f32 v121, v92, v101, v115
	v_fma_f32 v98, -v93, v101, v120
	v_fma_f32 v99, v93, v100, v121
	ds_read2st64_b32 v[112:113], v94 offset0:168 offset1:169
	s_waitcnt lgkmcnt(6)
	v_cvt_pk_bf16_f32 v97, v98, v99
	s_nop 0
	global_store_short v96, v97, s[40:41]
	global_store_short_d16_hi v96, v97, s[40:41] offset:128
	s_add_u32 s40, s40, s42
	s_addc_u32 s41, s41, s43
	v_fma_f32 v120, v92, v98, v116
	v_fma_f32 v121, v92, v99, v117
	v_fma_f32 v100, -v93, v99, v120
	v_fma_f32 v101, v93, v98, v121
	ds_read2st64_b32 v[114:115], v94 offset0:170 offset1:171
	s_waitcnt lgkmcnt(6)
	v_cvt_pk_bf16_f32 v97, v100, v101
	s_nop 0
	global_store_short v96, v97, s[40:41]
	global_store_short_d16_hi v96, v97, s[40:41] offset:128
	s_add_u32 s40, s40, s42
	s_addc_u32 s41, s41, s43
	v_fma_f32 v120, v92, v100, v118
	v_fma_f32 v121, v92, v101, v119
	v_fma_f32 v98, -v93, v101, v120
	v_fma_f32 v99, v93, v100, v121
	ds_read2st64_b32 v[116:117], v94 offset0:172 offset1:173
	s_waitcnt lgkmcnt(6)
; __device__ __forceinline__ bf16_t f2bf(float f) { return (bf16_t)(cvt_pk_bf16(f, 0.f) & 0xffffu); }
; __device__ __forceinline__ void scan_phase(const Ctx& X, const float* S, const float* AT, bf16_t* A2) {
;     ...
;     for (int c0 = 0; c0 < 128; c0 += 16) { float sr[16], si[16];
; #pragma unroll
;         for (int c = 0; c < 16; ++c) { const int cc = dir == 0 ? c0 + c : 127 - c0 - c; const size_t n = 128 * b + cc; sr[c] = Sg[n * 256]; si[c] = Sg[n * 256 + 64]; }
; #pragma unroll
;         for (int c = 0; c < 16; ++c) { const int cc = dir == 0 ? c0 + c : 127 - c0 - c; const size_t n = 128 * b + cc;
;             Hg[n * A2K] = f2bf(hr); Hg[n * A2K + 64] = f2bf(hi);
;             const float t = ar * hr - ai * hi + sr[c]; hi = ar * hi + ai * hr + si[c]; hr = t; } }
	v_cvt_pk_bf16_f32 v97, v98, v99
	s_nop 0
	global_store_short v96, v97, s[40:41]
	global_store_short_d16_hi v96, v97, s[40:41] offset:128
	s_add_u32 s40, s40, s42
	s_addc_u32 s41, s41, s43
	v_fma_f32 v120, v92, v98, v104
	v_fma_f32 v121, v92, v99, v105
	v_fma_f32 v100, -v93, v99, v120
	v_fma_f32 v101, v93, v98, v121
	ds_read2st64_b32 v[118:119], v94 offset0:174 offset1:175
	s_waitcnt lgkmcnt(6)
	v_cvt_pk_bf16_f32 v97, v100, v101
	s_nop 0
	global_store_short v96, v97, s[40:41]
	global_store_short_d16_hi v96, v97, s[40:41] offset:128
	s_add_u32 s40, s40, s42
	s_addc_u32 s41, s41, s43
	v_fma_f32 v120, v92, v100, v106
	v_fma_f32 v121, v92, v101, v107
	v_fma_f32 v98, -v93, v101, v120
	v_fma_f32 v99, v93, v100, v121
	ds_read2st64_b32 v[104:105], v94 offset0:176 offset1:177
	s_waitcnt lgkmcnt(6)
	v_cvt_pk_bf16_f32 v97, v98, v99
	s_nop 0
	global_store_short v96, v97, s[40:41]
	global_store_short_d16_hi v96, v97, s[40:41] offset:128
	s_add_u32 s40, s40, s42
	s_addc_u32 s41, s41, s43
	v_fma_f32 v120, v92, v98, v108
	v_fma_f32 v121, v92, v99, v109
	v_fma_f32 v100, -v93, v99, v120
	v_fma_f32 v101, v93, v98, v121
	ds_read2st64_b32 v[106:107], v94 offset0:178 offset1:179
	s_waitcnt lgkmcnt(6)
	v_cvt_pk_bf16_f32 v97, v100, v101
	s_nop 0
	global_store_short v96, v97, s[40:41]
	global_store_short_d16_hi v96, v97, s[40:41] offset:128
	s_add_u32 s40, s40, s42
	s_addc_u32 s41, s41, s43
	v_fma_f32 v120, v92, v100, v110
	v_fma_f32 v121, v92, v101, v111
	v_fma_f32 v98, -v93, v101, v120
	v_fma_f32 v99, v93, v100, v121
	ds_read2st64_b32 v[108:109], v94 offset0:180 offset1:181
	s_waitcnt lgkmcnt(6)
	v_cvt_pk_bf16_f32 v97, v98, v99
	s_nop 0
	global_store_short v96, v97, s[40:41]
	global_store_short_d16_hi v96, v97, s[40:41] offset:128
	s_add_u32 s40, s40, s42
	s_addc_u32 s41, s41, s43
	v_fma_f32 v120, v92, v98, v112
	v_fma_f32 v121, v92, v99, v113
	v_fma_f32 v100, -v93, v99, v120
	v_fma_f32 v101, v93, v98, v121
	ds_read2st64_b32 v[110:111], v94 offset0:182 offset1:183
	s_waitcnt lgkmcnt(6)
	v_cvt_pk_bf16_f32 v97, v100, v101
	s_nop 0
	global_store_short v96, v97, s[40:41]
	global_store_short_d16_hi v96, v97, s[40:41] offset:128
	s_add_u32 s40, s40, s42
	s_addc_u32 s41, s41, s43
	v_fma_f32 v120, v92, v100, v114
	v_fma_f32 v121, v92, v101, v115
	v_fma_f32 v98, -v93, v101, v120
	v_fma_f32 v99, v93, v100, v121
	ds_read2st64_b32 v[112:113], v94 offset0:184 offset1:185
	s_waitcnt lgkmcnt(6)
	v_cvt_pk_bf16_f32 v97, v98, v99
	s_nop 0
	global_store_short v96, v97, s[40:41]
	global_store_short_d16_hi v96, v97, s[40:41] offset:128
	s_add_u32 s40, s40, s42
	s_addc_u32 s41, s41, s43
	v_fma_f32 v120, v92, v98, v116
	v_fma_f32 v121, v92, v99, v117
	v_fma_f32 v100, -v93, v99, v120
	v_fma_f32 v101, v93, v98, v121
	ds_read2st64_b32 v[114:115], v94 offset0:186 offset1:187
	s_waitcnt lgkmcnt(6)
	v_cvt_pk_bf16_f32 v97, v100, v101
	s_nop 0
	global_store_short v96, v97, s[40:41]
	global_store_short_d16_hi v96, v97, s[40:41] offset:128
	s_add_u32 s40, s40, s42
	s_addc_u32 s41, s41, s43
	v_fma_f32 v120, v92, v100, v118
	v_fma_f32 v121, v92, v101, v119
	v_fma_f32 v98, -v93, v101, v120
	v_fma_f32 v99, v93, v100, v121
	ds_read2st64_b32 v[116:117], v94 offset0:188 offset1:189
	s_waitcnt lgkmcnt(6)
	v_cvt_pk_bf16_f32 v97, v98, v99
	s_nop 0
	global_store_short v96, v97, s[40:41]
	global_store_short_d16_hi v96, v97, s[40:41] offset:128
	s_add_u32 s40, s40, s42
	s_addc_u32 s41, s41, s43
	v_fma_f32 v120, v92, v98, v104
	v_fma_f32 v121, v92, v99, v105
	v_fma_f32 v100, -v93, v99, v120
	v_fma_f32 v101, v93, v98, v121
	ds_read2st64_b32 v[118:119], v94 offset0:190 offset1:191
	s_waitcnt lgkmcnt(6)
	v_cvt_pk_bf16_f32 v97, v100, v101
	s_nop 0
	global_store_short v96, v97, s[40:41]
	global_store_short_d16_hi v96, v97, s[40:41] offset:128
	s_add_u32 s40, s40, s42
	s_addc_u32 s41, s41, s43
	v_fma_f32 v120, v92, v100, v106
	v_fma_f32 v121, v92, v101, v107
	v_fma_f32 v98, -v93, v101, v120
	v_fma_f32 v99, v93, v100, v121
	ds_read2st64_b32 v[104:105], v94 offset0:192 offset1:193
	s_waitcnt lgkmcnt(6)
	v_cvt_pk_bf16_f32 v97, v98, v99
	s_nop 0
	global_store_short v96, v97, s[40:41]
	global_store_short_d16_hi v96, v97, s[40:41] offset:128
	s_add_u32 s40, s40, s42
	s_addc_u32 s41, s41, s43
	v_fma_f32 v120, v92, v98, v108
	v_fma_f32 v121, v92, v99, v109
	v_fma_f32 v100, -v93, v99, v120
	v_fma_f32 v101, v93, v98, v121
	ds_read2st64_b32 v[106:107], v94 offset0:194 offset1:195
	s_waitcnt lgkmcnt(6)
	v_cvt_pk_bf16_f32 v97, v100, v101
	s_nop 0
	global_store_short v96, v97, s[40:41]
	global_store_short_d16_hi v96, v97, s[40:41] offset:128
	s_add_u32 s40, s40, s42
	s_addc_u32 s41, s41, s43
	v_fma_f32 v120, v92, v100, v110
	v_fma_f32 v121, v92, v101, v111
	v_fma_f32 v98, -v93, v101, v120
	v_fma_f32 v99, v93, v100, v121
	ds_read2st64_b32 v[108:109], v94 offset0:196 offset1:197
	s_waitcnt lgkmcnt(6)
	v_cvt_pk_bf16_f32 v97, v98, v99
	s_nop 0
	global_store_short v96, v97, s[40:41]
	global_store_short_d16_hi v96, v97, s[40:41] offset:128
	s_add_u32 s40, s40, s42
	s_addc_u32 s41, s41, s43
	v_fma_f32 v120, v92, v98, v112
	v_fma_f32 v121, v92, v99, v113
	v_fma_f32 v100, -v93, v99, v120
	v_fma_f32 v101, v93, v98, v121
	ds_read2st64_b32 v[110:111], v94 offset0:198 offset1:199
	s_waitcnt lgkmcnt(6)
	v_cvt_pk_bf16_f32 v97, v100, v101
	s_nop 0
	global_store_short v96, v97, s[40:41]
	global_store_short_d16_hi v96, v97, s[40:41] offset:128
	s_add_u32 s40, s40, s42
	s_addc_u32 s41, s41, s43
	v_fma_f32 v120, v92, v100, v114
	v_fma_f32 v121, v92, v101, v115
	v_fma_f32 v98, -v93, v101, v120
	v_fma_f32 v99, v93, v100, v121
	ds_read2st64_b32 v[112:113], v94 offset0:200 offset1:201
	s_waitcnt lgkmcnt(6)
; __device__ __forceinline__ bf16_t f2bf(float f) { return (bf16_t)(cvt_pk_bf16(f, 0.f) & 0xffffu); }
; __device__ __forceinline__ void scan_phase(const Ctx& X, const float* S, const float* AT, bf16_t* A2) {
;     ...
;     for (int c0 = 0; c0 < 128; c0 += 16) { float sr[16], si[16];
; #pragma unroll
;         for (int c = 0; c < 16; ++c) { const int cc = dir == 0 ? c0 + c : 127 - c0 - c; const size_t n = 128 * b + cc; sr[c] = Sg[n * 256]; si[c] = Sg[n * 256 + 64]; }
; #pragma unroll
;         for (int c = 0; c < 16; ++c) { const int cc = dir == 0 ? c0 + c : 127 - c0 - c; const size_t n = 128 * b + cc;
;             Hg[n * A2K] = f2bf(hr); Hg[n * A2K + 64] = f2bf(hi);
;             const float t = ar * hr - ai * hi + sr[c]; hi = ar * hi + ai * hr + si[c]; hr = t; } }
	v_cvt_pk_bf16_f32 v97, v98, v99
	s_nop 0
	global_store_short v96, v97, s[40:41]
	global_store_short_d16_hi v96, v97, s[40:41] offset:128
	s_add_u32 s40, s40, s42
	s_addc_u32 s41, s41, s43
	v_fma_f32 v120, v92, v98, v116
	v_fma_f32 v121, v92, v99, v117
	v_fma_f32 v100, -v93, v99, v120
	v_fma_f32 v101, v93, v98, v121
	ds_read2st64_b32 v[114:115], v94 offset0:202 offset1:203
	s_waitcnt lgkmcnt(6)
	v_cvt_pk_bf16_f32 v97, v100, v101
	s_nop 0
	global_store_short v96, v97, s[40:41]
	global_store_short_d16_hi v96, v97, s[40:41] offset:128
	s_add_u32 s40, s40, s42
	s_addc_u32 s41, s41, s43
	v_fma_f32 v120, v92, v100, v118
	v_fma_f32 v121, v92, v101, v119
	v_fma_f32 v98, -v93, v101, v120
	v_fma_f32 v99, v93, v100, v121
	ds_read2st64_b32 v[116:117], v94 offset0:204 offset1:205
	s_waitcnt lgkmcnt(6)
	v_cvt_pk_bf16_f32 v97, v98, v99
	s_nop 0
	global_store_short v96, v97, s[40:41]
	global_store_short_d16_hi v96, v97, s[40:41] offset:128
	s_add_u32 s40, s40, s42
	s_addc_u32 s41, s41, s43
	v_fma_f32 v120, v92, v98, v104
	v_fma_f32 v121, v92, v99, v105
	v_fma_f32 v100, -v93, v99, v120
	v_fma_f32 v101, v93, v98, v121
	ds_read2st64_b32 v[118:119], v94 offset0:206 offset1:207
	s_waitcnt lgkmcnt(6)
	v_cvt_pk_bf16_f32 v97, v100, v101
	s_nop 0
	global_store_short v96, v97, s[40:41]
	global_store_short_d16_hi v96, v97, s[40:41] offset:128
	s_add_u32 s40, s40, s42
	s_addc_u32 s41, s41, s43
	v_fma_f32 v120, v92, v100, v106
	v_fma_f32 v121, v92, v101, v107
	v_fma_f32 v98, -v93, v101, v120
	v_fma_f32 v99, v93, v100, v121
	ds_read2st64_b32 v[104:105], v94 offset0:208 offset1:209
	s_waitcnt lgkmcnt(6)
	v_cvt_pk_bf16_f32 v97, v98, v99
	s_nop 0
	global_store_short v96, v97, s[40:41]
	global_store_short_d16_hi v96, v97, s[40:41] offset:128
	s_add_u32 s40, s40, s42
	s_addc_u32 s41, s41, s43
	v_fma_f32 v120, v92, v98, v108
	v_fma_f32 v121, v92, v99, v109
	v_fma_f32 v100, -v93, v99, v120
	v_fma_f32 v101, v93, v98, v121
	ds_read2st64_b32 v[106:107], v94 offset0:210 offset1:211
	s_waitcnt lgkmcnt(6)
	v_cvt_pk_bf16_f32 v97, v100, v101
	s_nop 0
	global_store_short v96, v97, s[40:41]
	global_store_short_d16_hi v96, v97, s[40:41] offset:128
	s_add_u32 s40, s40, s42
	s_addc_u32 s41, s41, s43
	v_fma_f32 v120, v92, v100, v110
	v_fma_f32 v121, v92, v101, v111
	v_fma_f32 v98, -v93, v101, v120
	v_fma_f32 v99, v93, v100, v121
	ds_read2st64_b32 v[108:109], v94 offset0:212 offset1:213
	s_waitcnt lgkmcnt(6)
	v_cvt_pk_bf16_f32 v97, v98, v99
	s_nop 0
	global_store_short v96, v97, s[40:41]
	global_store_short_d16_hi v96, v97, s[40:41] offset:128
	s_add_u32 s40, s40, s42
	s_addc_u32 s41, s41, s43
	v_fma_f32 v120, v92, v98, v112
	v_fma_f32 v121, v92, v99, v113
	v_fma_f32 v100, -v93, v99, v120
	v_fma_f32 v101, v93, v98, v121
	ds_read2st64_b32 v[110:111], v94 offset0:214 offset1:215
	s_waitcnt lgkmcnt(6)
	v_cvt_pk_bf16_f32 v97, v100, v101
	s_nop 0
	global_store_short v96, v97, s[40:41]
	global_store_short_d16_hi v96, v97, s[40:41] offset:128
	s_add_u32 s40, s40, s42
	s_addc_u32 s41, s41, s43
	v_fma_f32 v120, v92, v100, v114
	v_fma_f32 v121, v92, v101, v115
	v_fma_f32 v98, -v93, v101, v120
	v_fma_f32 v99, v93, v100, v121
	ds_read2st64_b32 v[112:113], v94 offset0:216 offset1:217
	s_waitcnt lgkmcnt(6)
	v_cvt_pk_bf16_f32 v97, v98, v99
	s_nop 0
	global_store_short v96, v97, s[40:41]
	global_store_short_d16_hi v96, v97, s[40:41] offset:128
	s_add_u32 s40, s40, s42
	s_addc_u32 s41, s41, s43
	v_fma_f32 v120, v92, v98, v116
	v_fma_f32 v121, v92, v99, v117
	v_fma_f32 v100, -v93, v99, v120
	v_fma_f32 v101, v93, v98, v121
	ds_read2st64_b32 v[114:115], v94 offset0:218 offset1:219
	s_waitcnt lgkmcnt(6)
	v_cvt_pk_bf16_f32 v97, v100, v101
	s_nop 0
	global_store_short v96, v97, s[40:41]
	global_store_short_d16_hi v96, v97, s[40:41] offset:128
	s_add_u32 s40, s40, s42
	s_addc_u32 s41, s41, s43
	v_fma_f32 v120, v92, v100, v118
	v_fma_f32 v121, v92, v101, v119
	v_fma_f32 v98, -v93, v101, v120
	v_fma_f32 v99, v93, v100, v121
	ds_read2st64_b32 v[116:117], v94 offset0:220 offset1:221
	s_waitcnt lgkmcnt(6)
	v_cvt_pk_bf16_f32 v97, v98, v99
	s_nop 0
	global_store_short v96, v97, s[40:41]
	global_store_short_d16_hi v96, v97, s[40:41] offset:128
	s_add_u32 s40, s40, s42
	s_addc_u32 s41, s41, s43
	v_fma_f32 v120, v92, v98, v104
	v_fma_f32 v121, v92, v99, v105
	v_fma_f32 v100, -v93, v99, v120
	v_fma_f32 v101, v93, v98, v121
	ds_read2st64_b32 v[118:119], v94 offset0:222 offset1:223
	s_waitcnt lgkmcnt(6)
	v_cvt_pk_bf16_f32 v97, v100, v101
	s_nop 0
	global_store_short v96, v97, s[40:41]
	global_store_short_d16_hi v96, v97, s[40:41] offset:128
	s_add_u32 s40, s40, s42
	s_addc_u32 s41, s41, s43
	v_fma_f32 v120, v92, v100, v106
	v_fma_f32 v121, v92, v101, v107
	v_fma_f32 v98, -v93, v101, v120
	v_fma_f32 v99, v93, v100, v121
	ds_read2st64_b32 v[104:105], v94 offset0:224 offset1:225
	s_waitcnt lgkmcnt(6)
	v_cvt_pk_bf16_f32 v97, v98, v99
	s_nop 0
	global_store_short v96, v97, s[40:41]
	global_store_short_d16_hi v96, v97, s[40:41] offset:128
	s_add_u32 s40, s40, s42
	s_addc_u32 s41, s41, s43
	v_fma_f32 v120, v92, v98, v108
	v_fma_f32 v121, v92, v99, v109
	v_fma_f32 v100, -v93, v99, v120
	v_fma_f32 v101, v93, v98, v121
	ds_read2st64_b32 v[106:107], v94 offset0:226 offset1:227
	s_waitcnt lgkmcnt(6)
	v_cvt_pk_bf16_f32 v97, v100, v101
	s_nop 0
	global_store_short v96, v97, s[40:41]
	global_store_short_d16_hi v96, v97, s[40:41] offset:128
	s_add_u32 s40, s40, s42
	s_addc_u32 s41, s41, s43
	v_fma_f32 v120, v92, v100, v110
	v_fma_f32 v121, v92, v101, v111
	v_fma_f32 v98, -v93, v101, v120
	v_fma_f32 v99, v93, v100, v121
	ds_read2st64_b32 v[108:109], v94 offset0:228 offset1:229
	s_waitcnt lgkmcnt(6)
; __device__ __forceinline__ bf16_t f2bf(float f) { return (bf16_t)(cvt_pk_bf16(f, 0.f) & 0xffffu); }
; __device__ __forceinline__ void scan_phase(const Ctx& X, const float* S, const float* AT, bf16_t* A2) {
;     ...
;     for (int c0 = 0; c0 < 128; c0 += 16) { float sr[16], si[16];
; #pragma unroll
;         for (int c = 0; c < 16; ++c) { const int cc = dir == 0 ? c0 + c : 127 - c0 - c; const size_t n = 128 * b + cc; sr[c] = Sg[n * 256]; si[c] = Sg[n * 256 + 64]; }
; #pragma unroll
;         for (int c = 0; c < 16; ++c) { const int cc = dir == 0 ? c0 + c : 127 - c0 - c; const size_t n = 128 * b + cc;
;             Hg[n * A2K] = f2bf(hr); Hg[n * A2K + 64] = f2bf(hi);
;             const float t = ar * hr - ai * hi + sr[c]; hi = ar * hi + ai * hr + si[c]; hr = t; } }
	v_cvt_pk_bf16_f32 v97, v98, v99
	s_nop 0
	global_store_short v96, v97, s[40:41]
	global_store_short_d16_hi v96, v97, s[40:41] offset:128
	s_add_u32 s40, s40, s42
	s_addc_u32 s41, s41, s43
	v_fma_f32 v120, v92, v98, v112
	v_fma_f32 v121, v92, v99, v113
	v_fma_f32 v100, -v93, v99, v120
	v_fma_f32 v101, v93, v98, v121
	ds_read2st64_b32 v[110:111], v94 offset0:230 offset1:231
	s_waitcnt lgkmcnt(6)
	v_cvt_pk_bf16_f32 v97, v100, v101
	s_nop 0
	global_store_short v96, v97, s[40:41]
	global_store_short_d16_hi v96, v97, s[40:41] offset:128
	s_add_u32 s40, s40, s42
	s_addc_u32 s41, s41, s43
	v_fma_f32 v120, v92, v100, v114
	v_fma_f32 v121, v92, v101, v115
	v_fma_f32 v98, -v93, v101, v120
	v_fma_f32 v99, v93, v100, v121
	ds_read2st64_b32 v[112:113], v94 offset0:232 offset1:233
	s_waitcnt lgkmcnt(6)
	v_cvt_pk_bf16_f32 v97, v98, v99
	s_nop 0
	global_store_short v96, v97, s[40:41]
	global_store_short_d16_hi v96, v97, s[40:41] offset:128
	s_add_u32 s40, s40, s42
	s_addc_u32 s41, s41, s43
	v_fma_f32 v120, v92, v98, v116
	v_fma_f32 v121, v92, v99, v117
	v_fma_f32 v100, -v93, v99, v120
	v_fma_f32 v101, v93, v98, v121
	ds_read2st64_b32 v[114:115], v94 offset0:234 offset1:235
	s_waitcnt lgkmcnt(6)
	v_cvt_pk_bf16_f32 v97, v100, v101
	s_nop 0
	global_store_short v96, v97, s[40:41]
	global_store_short_d16_hi v96, v97, s[40:41] offset:128
	s_add_u32 s40, s40, s42
	s_addc_u32 s41, s41, s43
	v_fma_f32 v120, v92, v100, v118
	v_fma_f32 v121, v92, v101, v119
	v_fma_f32 v98, -v93, v101, v120
	v_fma_f32 v99, v93, v100, v121
	ds_read2st64_b32 v[116:117], v94 offset0:236 offset1:237
	s_waitcnt lgkmcnt(6)
	v_cvt_pk_bf16_f32 v97, v98, v99
	s_nop 0
	global_store_short v96, v97, s[40:41]
	global_store_short_d16_hi v96, v97, s[40:41] offset:128
	s_add_u32 s40, s40, s42
	s_addc_u32 s41, s41, s43
	v_fma_f32 v120, v92, v98, v104
	v_fma_f32 v121, v92, v99, v105
	v_fma_f32 v100, -v93, v99, v120
	v_fma_f32 v101, v93, v98, v121
	ds_read2st64_b32 v[118:119], v94 offset0:238 offset1:239
	s_waitcnt lgkmcnt(6)
	v_cvt_pk_bf16_f32 v97, v100, v101
	s_nop 0
	global_store_short v96, v97, s[40:41]
	global_store_short_d16_hi v96, v97, s[40:41] offset:128
	s_add_u32 s40, s40, s42
	s_addc_u32 s41, s41, s43
	v_fma_f32 v120, v92, v100, v106
	v_fma_f32 v121, v92, v101, v107
	v_fma_f32 v98, -v93, v101, v120
	v_fma_f32 v99, v93, v100, v121
	ds_read2st64_b32 v[104:105], v94 offset0:240 offset1:241
	s_waitcnt lgkmcnt(6)
	v_cvt_pk_bf16_f32 v97, v98, v99
	s_nop 0
	global_store_short v96, v97, s[40:41]
	global_store_short_d16_hi v96, v97, s[40:41] offset:128
	s_add_u32 s40, s40, s42
	s_addc_u32 s41, s41, s43
	v_fma_f32 v120, v92, v98, v108
	v_fma_f32 v121, v92, v99, v109
	v_fma_f32 v100, -v93, v99, v120
	v_fma_f32 v101, v93, v98, v121
	ds_read2st64_b32 v[106:107], v94 offset0:242 offset1:243
	s_waitcnt lgkmcnt(6)
	v_cvt_pk_bf16_f32 v97, v100, v101
	s_nop 0
	global_store_short v96, v97, s[40:41]
	global_store_short_d16_hi v96, v97, s[40:41] offset:128
	s_add_u32 s40, s40, s42
	s_addc_u32 s41, s41, s43
	v_fma_f32 v120, v92, v100, v110
	v_fma_f32 v121, v92, v101, v111
	v_fma_f32 v98, -v93, v101, v120
	v_fma_f32 v99, v93, v100, v121
	ds_read2st64_b32 v[108:109], v94 offset0:244 offset1:245
	s_waitcnt lgkmcnt(6)
	v_cvt_pk_bf16_f32 v97, v98, v99
	s_nop 0
	global_store_short v96, v97, s[40:41]
	global_store_short_d16_hi v96, v97, s[40:41] offset:128
	s_add_u32 s40, s40, s42
	s_addc_u32 s41, s41, s43
	v_fma_f32 v120, v92, v98, v112
	v_fma_f32 v121, v92, v99, v113
	v_fma_f32 v100, -v93, v99, v120
	v_fma_f32 v101, v93, v98, v121
	ds_read2st64_b32 v[110:111], v94 offset0:246 offset1:247
	s_waitcnt lgkmcnt(6)
	v_cvt_pk_bf16_f32 v97, v100, v101
	s_nop 0
	global_store_short v96, v97, s[40:41]
	global_store_short_d16_hi v96, v97, s[40:41] offset:128
	s_add_u32 s40, s40, s42
	s_addc_u32 s41, s41, s43
	v_fma_f32 v120, v92, v100, v114
	v_fma_f32 v121, v92, v101, v115
	v_fma_f32 v98, -v93, v101, v120
	v_fma_f32 v99, v93, v100, v121
	ds_read2st64_b32 v[112:113], v94 offset0:248 offset1:249
	s_waitcnt lgkmcnt(6)
	v_cvt_pk_bf16_f32 v97, v98, v99
	s_nop 0
	global_store_short v96, v97, s[40:41]
	global_store_short_d16_hi v96, v97, s[40:41] offset:128
	s_add_u32 s40, s40, s42
	s_addc_u32 s41, s41, s43
	v_fma_f32 v120, v92, v98, v116
	v_fma_f32 v121, v92, v99, v117
	v_fma_f32 v100, -v93, v99, v120
	v_fma_f32 v101, v93, v98, v121
	ds_read2st64_b32 v[114:115], v94 offset0:250 offset1:251
	s_waitcnt lgkmcnt(6)
	v_cvt_pk_bf16_f32 v97, v100, v101
	s_nop 0
	global_store_short v96, v97, s[40:41]
	global_store_short_d16_hi v96, v97, s[40:41] offset:128
	s_add_u32 s40, s40, s42
	s_addc_u32 s41, s41, s43
	v_fma_f32 v120, v92, v100, v118
	v_fma_f32 v121, v92, v101, v119
	v_fma_f32 v98, -v93, v101, v120
	v_fma_f32 v99, v93, v100, v121
	ds_read2st64_b32 v[116:117], v94 offset0:252 offset1:253
	s_waitcnt lgkmcnt(6)
	v_cvt_pk_bf16_f32 v97, v98, v99
	s_nop 0
	global_store_short v96, v97, s[40:41]
	global_store_short_d16_hi v96, v97, s[40:41] offset:128
	s_add_u32 s40, s40, s42
	s_addc_u32 s41, s41, s43
	v_fma_f32 v120, v92, v98, v104
	v_fma_f32 v121, v92, v99, v105
	v_fma_f32 v100, -v93, v99, v120
	v_fma_f32 v101, v93, v98, v121
	ds_read2st64_b32 v[118:119], v94 offset0:254 offset1:255
	s_waitcnt lgkmcnt(6)
	v_cvt_pk_bf16_f32 v97, v100, v101
	s_nop 0
	global_store_short v96, v97, s[40:41]
	global_store_short_d16_hi v96, v97, s[40:41] offset:128
	s_add_u32 s40, s40, s42
	s_addc_u32 s41, s41, s43
	v_fma_f32 v120, v92, v100, v106
	v_fma_f32 v121, v92, v101, v107
	v_fma_f32 v98, -v93, v101, v120
	v_fma_f32 v99, v93, v100, v121
	ds_read2st64_b32 v[104:105], v95 offset0:0 offset1:1
	s_waitcnt lgkmcnt(6)
; __device__ __forceinline__ bf16_t f2bf(float f) { return (bf16_t)(cvt_pk_bf16(f, 0.f) & 0xffffu); }
; __device__ __forceinline__ void scan_phase(const Ctx& X, const float* S, const float* AT, bf16_t* A2) {
;     ...
;     for (int c0 = 0; c0 < 128; c0 += 16) { float sr[16], si[16];
; #pragma unroll
;         for (int c = 0; c < 16; ++c) { const int cc = dir == 0 ? c0 + c : 127 - c0 - c; const size_t n = 128 * b + cc; sr[c] = Sg[n * 256]; si[c] = Sg[n * 256 + 64]; }
; #pragma unroll
;         for (int c = 0; c < 16; ++c) { const int cc = dir == 0 ? c0 + c : 127 - c0 - c; const size_t n = 128 * b + cc;
;             Hg[n * A2K] = f2bf(hr); Hg[n * A2K + 64] = f2bf(hi);
;             const float t = ar * hr - ai * hi + sr[c]; hi = ar * hi + ai * hr + si[c]; hr = t; } }
; }
	v_cvt_pk_bf16_f32 v97, v98, v99
	s_nop 0
	global_store_short v96, v97, s[40:41]
	global_store_short_d16_hi v96, v97, s[40:41] offset:128
	s_add_u32 s40, s40, s42
	s_addc_u32 s41, s41, s43
	v_fma_f32 v120, v92, v98, v108
	v_fma_f32 v121, v92, v99, v109
	v_fma_f32 v100, -v93, v99, v120
	v_fma_f32 v101, v93, v98, v121
	ds_read2st64_b32 v[106:107], v95 offset0:2 offset1:3
	s_waitcnt lgkmcnt(6)
	v_cvt_pk_bf16_f32 v97, v100, v101
	s_nop 0
	global_store_short v96, v97, s[40:41]
	global_store_short_d16_hi v96, v97, s[40:41] offset:128
	s_add_u32 s40, s40, s42
	s_addc_u32 s41, s41, s43
	v_fma_f32 v120, v92, v100, v110
	v_fma_f32 v121, v92, v101, v111
	v_fma_f32 v98, -v93, v101, v120
	v_fma_f32 v99, v93, v100, v121
	ds_read2st64_b32 v[108:109], v95 offset0:4 offset1:5
	s_waitcnt lgkmcnt(6)
	v_cvt_pk_bf16_f32 v97, v98, v99
	s_nop 0
	global_store_short v96, v97, s[40:41]
	global_store_short_d16_hi v96, v97, s[40:41] offset:128
	s_add_u32 s40, s40, s42
	s_addc_u32 s41, s41, s43
	v_fma_f32 v120, v92, v98, v112
	v_fma_f32 v121, v92, v99, v113
	v_fma_f32 v100, -v93, v99, v120
	v_fma_f32 v101, v93, v98, v121
	ds_read2st64_b32 v[110:111], v95 offset0:6 offset1:7
	s_waitcnt lgkmcnt(6)
	v_cvt_pk_bf16_f32 v97, v100, v101
	s_nop 0
	global_store_short v96, v97, s[40:41]
	global_store_short_d16_hi v96, v97, s[40:41] offset:128
	s_add_u32 s40, s40, s42
	s_addc_u32 s41, s41, s43
	v_fma_f32 v120, v92, v100, v114
	v_fma_f32 v121, v92, v101, v115
	v_fma_f32 v98, -v93, v101, v120
	v_fma_f32 v99, v93, v100, v121
	ds_read2st64_b32 v[112:113], v95 offset0:8 offset1:9
	s_waitcnt lgkmcnt(6)
	v_cvt_pk_bf16_f32 v97, v98, v99
	s_nop 0
	global_store_short v96, v97, s[40:41]
	global_store_short_d16_hi v96, v97, s[40:41] offset:128
	s_add_u32 s40, s40, s42
	s_addc_u32 s41, s41, s43
	v_fma_f32 v120, v92, v98, v116
	v_fma_f32 v121, v92, v99, v117
	v_fma_f32 v100, -v93, v99, v120
	v_fma_f32 v101, v93, v98, v121
	ds_read2st64_b32 v[114:115], v95 offset0:10 offset1:11
	s_waitcnt lgkmcnt(6)
	v_cvt_pk_bf16_f32 v97, v100, v101
	s_nop 0
	global_store_short v96, v97, s[40:41]
	global_store_short_d16_hi v96, v97, s[40:41] offset:128
	s_add_u32 s40, s40, s42
	s_addc_u32 s41, s41, s43
	v_fma_f32 v120, v92, v100, v118
	v_fma_f32 v121, v92, v101, v119
	v_fma_f32 v98, -v93, v101, v120
	v_fma_f32 v99, v93, v100, v121
	ds_read2st64_b32 v[116:117], v95 offset0:12 offset1:13
	s_waitcnt lgkmcnt(6)
	v_cvt_pk_bf16_f32 v97, v98, v99
	s_nop 0
	global_store_short v96, v97, s[40:41]
	global_store_short_d16_hi v96, v97, s[40:41] offset:128
	s_add_u32 s40, s40, s42
	s_addc_u32 s41, s41, s43
	v_fma_f32 v120, v92, v98, v104
	v_fma_f32 v121, v92, v99, v105
	v_fma_f32 v100, -v93, v99, v120
	v_fma_f32 v101, v93, v98, v121
	ds_read2st64_b32 v[118:119], v95 offset0:14 offset1:15
	s_waitcnt lgkmcnt(6)
	v_cvt_pk_bf16_f32 v97, v100, v101
	s_nop 0
	global_store_short v96, v97, s[40:41]
	global_store_short_d16_hi v96, v97, s[40:41] offset:128
	s_add_u32 s40, s40, s42
	s_addc_u32 s41, s41, s43
	v_fma_f32 v120, v92, v100, v106
	v_fma_f32 v121, v92, v101, v107
	v_fma_f32 v98, -v93, v101, v120
	v_fma_f32 v99, v93, v100, v121
	s_waitcnt lgkmcnt(5)
	v_cvt_pk_bf16_f32 v97, v98, v99
	s_nop 0
	global_store_short v96, v97, s[40:41]
	global_store_short_d16_hi v96, v97, s[40:41] offset:128
	s_add_u32 s40, s40, s42
	s_addc_u32 s41, s41, s43
	v_fma_f32 v120, v92, v98, v108
	v_fma_f32 v121, v92, v99, v109
	v_fma_f32 v100, -v93, v99, v120
	v_fma_f32 v101, v93, v98, v121
	s_waitcnt lgkmcnt(4)
	v_cvt_pk_bf16_f32 v97, v100, v101
	s_nop 0
	global_store_short v96, v97, s[40:41]
	global_store_short_d16_hi v96, v97, s[40:41] offset:128
	s_add_u32 s40, s40, s42
	s_addc_u32 s41, s41, s43
	v_fma_f32 v120, v92, v100, v110
	v_fma_f32 v121, v92, v101, v111
	v_fma_f32 v98, -v93, v101, v120
	v_fma_f32 v99, v93, v100, v121
	s_waitcnt lgkmcnt(3)
	v_cvt_pk_bf16_f32 v97, v98, v99
	s_nop 0
	global_store_short v96, v97, s[40:41]
	global_store_short_d16_hi v96, v97, s[40:41] offset:128
	s_add_u32 s40, s40, s42
	s_addc_u32 s41, s41, s43
	v_fma_f32 v120, v92, v98, v112
	v_fma_f32 v121, v92, v99, v113
	v_fma_f32 v100, -v93, v99, v120
	v_fma_f32 v101, v93, v98, v121
	s_waitcnt lgkmcnt(2)
	v_cvt_pk_bf16_f32 v97, v100, v101
	s_nop 0
	global_store_short v96, v97, s[40:41]
	global_store_short_d16_hi v96, v97, s[40:41] offset:128
	s_add_u32 s40, s40, s42
	s_addc_u32 s41, s41, s43
	v_fma_f32 v120, v92, v100, v114
	v_fma_f32 v121, v92, v101, v115
	v_fma_f32 v98, -v93, v101, v120
	v_fma_f32 v99, v93, v100, v121
	s_waitcnt lgkmcnt(1)
	v_cvt_pk_bf16_f32 v97, v98, v99
	s_nop 0
	global_store_short v96, v97, s[40:41]
	global_store_short_d16_hi v96, v97, s[40:41] offset:128
	s_add_u32 s40, s40, s42
	s_addc_u32 s41, s41, s43
	v_fma_f32 v120, v92, v98, v116
	v_fma_f32 v121, v92, v99, v117
	v_fma_f32 v100, -v93, v99, v120
	v_fma_f32 v101, v93, v98, v121
	s_waitcnt lgkmcnt(0)
	v_cvt_pk_bf16_f32 v97, v100, v101
	s_nop 0
	global_store_short v96, v97, s[40:41]
	global_store_short_d16_hi v96, v97, s[40:41] offset:128
	s_add_u32 s40, s40, s42
	s_addc_u32 s41, s41, s43
	v_fma_f32 v120, v92, v100, v118
	v_fma_f32 v121, v92, v101, v119
	v_fma_f32 v98, -v93, v101, v120
	v_fma_f32 v99, v93, v100, v121
.Lat_scan_done:
	s_barrier
.LBB0_696:
	s_or_b64 exec, exec, s[4:5]
	s_add_u32 s6, s88, 0x1a600000
	s_addc_u32 s7, s89, 0
	v_mov_b32_e32 v0, v206
	s_cmpk_gt_i32 s2, 0x3ff
	v_readfirstlane_b32 s0, v0
	s_cbranch_scc1 .LBB0_705
	s_ashr_i32 s21, s0, 7
	s_lshr_b32 s0, s0, 1
	s_and_b32 s28, s0, 32
	v_ashrrev_i32_e32 v122, 3, v0
	s_movk_i32 s0, 0x2200
	v_mov_b64_e32 v[2:3], s[24:25]
	v_and_b32_e32 v1, 63, v0
	v_and_b32_e32 v121, 15, v0
	v_bfe_u32 v4, v0, 4, 2
	v_and_b32_e32 v68, 48, v0
	v_lshlrev_b32_e32 v0, 3, v0
	v_mad_i64_i32 v[72:73], s[0:1], v122, s0, v[2:3]
	v_and_b32_e32 v0, 56, v0
	s_movk_i32 s0, 0x90
	v_mul_lo_u32 v2, v122, s0
	v_lshlrev_b32_e32 v3, 1, v0
	v_add3_u32 v123, 0, v2, v3
	v_mov_b32_e32 v2, 0xffffff7f
	v_lshl_add_u32 v124, v4, 2, v2
	v_mbcnt_hi_u32_b32 v2, -1, v207
	v_lshlrev_b32_e32 v64, 3, v4
	v_mov_b32_e32 v67, 0
	v_and_b32_e32 v4, 64, v2
	v_mov_b32_e32 v69, v67
	v_cmp_gt_u32_e32 vcc, 16, v1
	v_xor_b32_e32 v3, 16, v2
	v_add_u32_e32 v4, 64, v4
	v_lshl_add_u64 v[70:71], s[26:27], 0, v[68:69]
	v_cndmask_b32_e64 v69, 0, 1.0, vcc
	v_cmp_lt_i32_e32 vcc, v3, v4
	v_mov_b32_e32 v65, v67
	v_or_b32_e32 v1, 48, v1
	v_cndmask_b32_e32 v3, v2, v3, vcc
	v_lshlrev_b32_e32 v125, 2, v3
	v_xor_b32_e32 v3, 32, v2
	v_cmp_lt_i32_e32 vcc, v3, v4
	s_mov_b32 s5, 0
	v_mul_u32_u24_e32 v127, 0x90, v121
	v_cndmask_b32_e32 v2, v2, v3, vcc
	v_lshlrev_b32_e32 v126, 2, v2
	v_mul_u32_u24_e32 v128, 0x90, v1
	v_lshl_add_u64 v[74:75], s[6:7], 0, v[64:65]
	v_lshlrev_b32_e32 v66, 1, v0
	v_mov_b32_e32 v65, 0x88000
	s_movk_i32 s24, 0xfefe
	s_mov_b32 s25, 0xff61b1e6
	v_mov_b32_e32 v129, 0xf149f2ca
	s_mov_b32 s26, s2
	s_branch .LBB0_699
